# grid barrier: last XCD leader bumps all XGEN words directly (no TOPGEN hop)
# baseline (speedup 1.0000x reference)
.LBB0_55:
	s_andn2_saveexec_b64 s[2:3], s[2:3]
	s_cbranch_execz .LBB0_75
	v_mov_b32_e32 v20, v1
	buffer_wbl2 sc1
	s_waitcnt lgkmcnt(0)
	s_waitcnt vmcnt(0)
	v_readlane_b32 s2, v251, 43
	v_readlane_b32 s3, v251, 44
	v_mov_b32_e32 v2, 1
	s_nop 4
	global_atomic_add v2, v193, v2, s[2:3] sc0
	s_waitcnt vmcnt(0)
	s_nop 0
	v_readfirstlane_b32 s4, v2
	v_readfirstlane_b32 s5, v0
	s_nop 3
	s_add_i32 s4, s4, 1
	s_mov_b32 s10, 11
.Lxb_mod:
	s_lshl_b32 s11, s5, s10
	s_cmp_ge_u32 s4, s11
	s_cselect_b32 s11, s11, 0
	s_sub_u32 s4, s4, s11
	s_add_i32 s10, s10, -1
	s_cmp_ge_i32 s10, 0
	s_cbranch_scc1 .Lxb_mod
	s_cmp_eq_u32 s4, 0
	s_cbranch_scc1 .Lxb_last
	buffer_inv sc1
	v_readlane_b32 s4, v251, 41
	v_readlane_b32 s5, v251, 42
	s_mov_b32 s31, 0
	s_nop 4
.Lxb_spin:
	global_load_dword v0, v193, s[4:5] sc1
	s_waitcnt vmcnt(0)
	v_cmp_ne_u32_e32 vcc, v0, v20
	s_cbranch_vccnz .Lxb_done
	s_sleep 1
	s_add_i32 s31, s31, 1
	s_cmp_lt_u32 s31, 0x400000
	s_cbranch_scc1 .Lxb_spin
	s_branch .Lxb_done
.Lxb_last:
	v_readlane_b32 s4, v251, 5
	v_readlane_b32 s5, v251, 6
	v_mov_b32_e32 v2, 1
	s_nop 3
	s_add_u32 s4, s4, 0x2200
	s_addc_u32 s5, s5, 0
	global_atomic_add v193, v2, s[4:5]
	global_atomic_add v193, v2, s[4:5] offset:256
	global_atomic_add v193, v2, s[4:5] offset:512
	global_atomic_add v193, v2, s[4:5] offset:768
	global_atomic_add v193, v2, s[4:5] offset:1024
	global_atomic_add v193, v2, s[4:5] offset:1280
	global_atomic_add v193, v2, s[4:5] offset:1536
	global_atomic_add v193, v2, s[4:5] offset:1792
	global_atomic_add v193, v2, s[4:5] offset:2048
	global_atomic_add v193, v2, s[4:5] offset:2304
	global_atomic_add v193, v2, s[4:5] offset:2560
	global_atomic_add v193, v2, s[4:5] offset:2816
	global_atomic_add v193, v2, s[4:5] offset:3072
	global_atomic_add v193, v2, s[4:5] offset:3328
	global_atomic_add v193, v2, s[4:5] offset:3584
	global_atomic_add v193, v2, s[4:5] offset:3840
	buffer_inv sc1
.Lxb_done:
	s_waitcnt vmcnt(0)
.LBB0_75:
	s_or_b64 exec, exec, s[0:1]
	s_waitcnt lgkmcnt(0)
	s_barrier
